# IN phase: waves 0-3 keep s_setprio 1 through the GEMM epilogues too (reset at the phase-loop tail instead of after each K-loop)
# speedup vs baseline: 1.0057x; 1.0057x over previous
.Lmy_prio_in:
.LBB0_920:
	s_add_u32 s2, s70, 0xfffc0080
	s_addc_u32 s3, s71, -1
	s_add_i32 s9, 0, 0x10000
	s_cmp_eq_u32 vcc_hi, 12
	s_cselect_b32 s75, s14, s3
	s_cselect_b32 s74, s24, s2
	s_cselect_b32 s73, s59, vcc_lo
	s_cselect_b32 s72, s61, s63
	s_add_i32 s0, 0, 0x14000
	s_add_i32 m0, s69, 0xc000
	s_nop 0
	global_load_lds_dwordx4 v172, s[70:71]
	s_add_i32 m0, s69, 0xe000
	s_nop 0
	global_load_lds_dwordx4 v174, s[70:71]
	v_add_u32_e32 v2, s9, v188
	ds_read_b128 v[132:135], v2
	ds_read_b128 v[136:139], v2 offset:1024
	ds_read_b128 v[140:143], v2 offset:2048
	ds_read_b128 v[144:147], v2 offset:3072
	v_add_u32_e32 v2, s0, v188
	ds_read_b128 v[148:151], v2
	ds_read_b128 v[152:155], v2 offset:1024
	ds_read_b128 v[156:159], v2 offset:2048
	ds_read_b128 v[160:163], v2 offset:3072
	v_lshl_add_u64 v[184:185], s[70:71], 0, v[172:173]
	ds_read_b128 v[176:179], v189
	ds_read_b128 v[180:183], v189 offset:1024
	ds_read_b128 v[198:201], v189 offset:2048
	ds_read_b128 v[202:205], v189 offset:3072
	ds_read_b128 v[206:209], v189 offset:4096
	ds_read_b128 v[210:213], v189 offset:5120
	ds_read_b128 v[214:217], v189 offset:6144
	ds_read_b128 v[218:221], v189 offset:7168
	v_lshl_add_u64 v[184:185], s[70:71], 0, v[174:175]
	s_waitcnt vmcnt(8)
	s_waitcnt lgkmcnt(0)
	s_barrier
	s_waitcnt lgkmcnt(0)
	v_mfma_f32_16x16x32_bf16 v[128:131], v[132:135], v[176:179], v[128:131]
	v_mfma_f32_16x16x32_bf16 v[124:127], v[140:143], v[176:179], v[124:127]
	v_mfma_f32_16x16x32_bf16 v[112:115], v[132:135], v[198:201], v[112:115]
	v_mfma_f32_16x16x32_bf16 v[108:111], v[140:143], v[198:201], v[108:111]
	v_mfma_f32_16x16x32_bf16 v[96:99], v[132:135], v[206:209], v[96:99]
	v_mfma_f32_16x16x32_bf16 v[92:95], v[140:143], v[206:209], v[92:95]
	v_mfma_f32_16x16x32_bf16 v[80:83], v[132:135], v[214:217], v[80:83]
	v_mfma_f32_16x16x32_bf16 v[76:79], v[140:143], v[214:217], v[76:79]
	v_mfma_f32_16x16x32_bf16 v[128:131], v[136:139], v[180:183], v[128:131]
	v_mfma_f32_16x16x32_bf16 v[124:127], v[144:147], v[180:183], v[124:127]
	v_mfma_f32_16x16x32_bf16 v[112:115], v[136:139], v[202:205], v[112:115]
	v_mfma_f32_16x16x32_bf16 v[108:111], v[144:147], v[202:205], v[108:111]
	v_mfma_f32_16x16x32_bf16 v[96:99], v[136:139], v[210:213], v[96:99]
	v_mfma_f32_16x16x32_bf16 v[92:95], v[144:147], v[210:213], v[92:95]
	v_mfma_f32_16x16x32_bf16 v[80:83], v[136:139], v[218:221], v[80:83]
	v_mfma_f32_16x16x32_bf16 v[76:79], v[144:147], v[218:221], v[76:79]
	v_mfma_f32_16x16x32_bf16 v[120:123], v[148:151], v[176:179], v[120:123]
	v_mfma_f32_16x16x32_bf16 v[116:119], v[156:159], v[176:179], v[116:119]
	v_mfma_f32_16x16x32_bf16 v[104:107], v[148:151], v[198:201], v[104:107]
	v_mfma_f32_16x16x32_bf16 v[100:103], v[156:159], v[198:201], v[100:103]
	v_mfma_f32_16x16x32_bf16 v[88:91], v[148:151], v[206:209], v[88:91]
	v_mfma_f32_16x16x32_bf16 v[84:87], v[156:159], v[206:209], v[84:87]
	v_mfma_f32_16x16x32_bf16 v[72:75], v[148:151], v[214:217], v[72:75]
	v_mfma_f32_16x16x32_bf16 v[68:71], v[156:159], v[214:217], v[68:71]
	v_mfma_f32_16x16x32_bf16 v[120:123], v[152:155], v[180:183], v[120:123]
	v_mfma_f32_16x16x32_bf16 v[116:119], v[160:163], v[180:183], v[116:119]
	v_mfma_f32_16x16x32_bf16 v[104:107], v[152:155], v[202:205], v[104:107]
	v_mfma_f32_16x16x32_bf16 v[100:103], v[160:163], v[202:205], v[100:103]
	v_mfma_f32_16x16x32_bf16 v[88:91], v[152:155], v[210:213], v[88:91]
	v_mfma_f32_16x16x32_bf16 v[84:87], v[160:163], v[210:213], v[84:87]
	v_mfma_f32_16x16x32_bf16 v[72:75], v[152:155], v[218:221], v[72:75]
	v_mfma_f32_16x16x32_bf16 v[68:71], v[160:163], v[218:221], v[68:71]
	s_barrier
	s_add_i32 s2, s9, s80
	s_mov_b32 m0, s2
	s_nop 0
	global_load_lds_dwordx4 v166, s[72:73]
	s_add_i32 m0, s2, 0x2000
	s_add_u32 s2, s72, 0x40000
	s_addc_u32 s3, s73, 0
	s_add_i32 s0, s0, s80
	global_load_lds_dwordx4 v170, s[72:73]
	s_mov_b32 m0, s0
	s_nop 0
	global_load_lds_dwordx4 v166, s[2:3]
	s_add_i32 m0, s0, 0x2000
	s_nop 0
	global_load_lds_dwordx4 v170, s[2:3]
	s_mov_b32 m0, s69
	s_nop 0
	global_load_lds_dwordx4 v164, s[74:75]
	s_mov_b32 m0, s81
	s_nop 0
	global_load_lds_dwordx4 v168, s[74:75]
	v_lshl_add_u64 v[184:185], s[72:73], 0, v[166:167]
	ds_read_b128 v[176:179], v189 offset:16384
	ds_read_b128 v[180:183], v189 offset:17408
	ds_read_b128 v[198:201], v189 offset:18432
	ds_read_b128 v[202:205], v189 offset:19456
	ds_read_b128 v[206:209], v189 offset:20480
	ds_read_b128 v[210:213], v189 offset:21504
	ds_read_b128 v[214:217], v189 offset:22528
	ds_read_b128 v[218:221], v189 offset:23552
	v_lshl_add_u64 v[190:191], s[72:73], 0, v[170:171]
	v_lshl_add_u64 v[222:223], s[2:3], 0, v[166:167]
	v_lshl_add_u64 v[224:225], s[74:75], 0, v[168:169]
	v_lshl_add_u64 v[222:223], s[2:3], 0, v[170:171]
	v_lshl_add_u64 v[222:223], s[74:75], 0, v[164:165]
	s_waitcnt vmcnt(8)
	s_waitcnt lgkmcnt(0)
	s_barrier
	s_waitcnt lgkmcnt(0)
	v_mfma_f32_16x16x32_bf16 v[64:67], v[132:135], v[176:179], v[64:67]
	v_mfma_f32_16x16x32_bf16 v[60:63], v[140:143], v[176:179], v[60:63]
	v_mfma_f32_16x16x32_bf16 v[48:51], v[132:135], v[198:201], v[48:51]
	v_mfma_f32_16x16x32_bf16 v[44:47], v[140:143], v[198:201], v[44:47]
	v_mfma_f32_16x16x32_bf16 v[32:35], v[132:135], v[206:209], v[32:35]
	v_mfma_f32_16x16x32_bf16 v[28:31], v[140:143], v[206:209], v[28:31]
	v_mfma_f32_16x16x32_bf16 v[16:19], v[132:135], v[214:217], v[16:19]
	v_mfma_f32_16x16x32_bf16 v[12:15], v[140:143], v[214:217], v[12:15]
	v_mfma_f32_16x16x32_bf16 v[64:67], v[136:139], v[180:183], v[64:67]
	v_mfma_f32_16x16x32_bf16 v[60:63], v[144:147], v[180:183], v[60:63]
	v_mfma_f32_16x16x32_bf16 v[48:51], v[136:139], v[202:205], v[48:51]
	v_mfma_f32_16x16x32_bf16 v[44:47], v[144:147], v[202:205], v[44:47]
	v_mfma_f32_16x16x32_bf16 v[32:35], v[136:139], v[210:213], v[32:35]
	v_mfma_f32_16x16x32_bf16 v[28:31], v[144:147], v[210:213], v[28:31]
	v_mfma_f32_16x16x32_bf16 v[16:19], v[136:139], v[218:221], v[16:19]
	v_mfma_f32_16x16x32_bf16 v[12:15], v[144:147], v[218:221], v[12:15]
	v_mfma_f32_16x16x32_bf16 v[56:59], v[148:151], v[176:179], v[56:59]
	v_mfma_f32_16x16x32_bf16 v[52:55], v[156:159], v[176:179], v[52:55]
	v_mfma_f32_16x16x32_bf16 v[40:43], v[148:151], v[198:201], v[40:43]
	v_mfma_f32_16x16x32_bf16 v[36:39], v[156:159], v[198:201], v[36:39]
	v_mfma_f32_16x16x32_bf16 v[24:27], v[148:151], v[206:209], v[24:27]
	v_mfma_f32_16x16x32_bf16 v[20:23], v[156:159], v[206:209], v[20:23]
	v_mfma_f32_16x16x32_bf16 v[8:11], v[148:151], v[214:217], v[8:11]
	v_mfma_f32_16x16x32_bf16 v[4:7], v[156:159], v[214:217], v[4:7]
	v_mfma_f32_16x16x32_bf16 v[56:59], v[152:155], v[180:183], v[56:59]
	v_mfma_f32_16x16x32_bf16 v[52:55], v[160:163], v[180:183], v[52:55]
	v_mfma_f32_16x16x32_bf16 v[40:43], v[152:155], v[202:205], v[40:43]
	v_mfma_f32_16x16x32_bf16 v[36:39], v[160:163], v[202:205], v[36:39]
	v_mfma_f32_16x16x32_bf16 v[24:27], v[152:155], v[210:213], v[24:27]
	v_mfma_f32_16x16x32_bf16 v[20:23], v[160:163], v[210:213], v[20:23]
	v_mfma_f32_16x16x32_bf16 v[8:11], v[152:155], v[218:221], v[8:11]
	v_mfma_f32_16x16x32_bf16 v[4:7], v[160:163], v[218:221], v[4:7]
	s_barrier
	s_add_i32 s0, 0, 0x18000
	s_add_i32 s9, 0, 0x1c000
	s_add_u32 s2, s74, 0x40000
	s_addc_u32 s3, s75, 0
	s_mov_b32 m0, s88
	s_nop 0
	global_load_lds_dwordx4 v164, s[2:3]
	s_mov_b32 m0, s89
	s_nop 0
	global_load_lds_dwordx4 v168, s[2:3]
	v_add_u32_e32 v2, s0, v188
	ds_read_b128 v[132:135], v2
	ds_read_b128 v[136:139], v2 offset:1024
	ds_read_b128 v[140:143], v2 offset:2048
	ds_read_b128 v[144:147], v2 offset:3072
	v_add_u32_e32 v2, s9, v188
	ds_read_b128 v[148:151], v2
	ds_read_b128 v[152:155], v2 offset:1024
	ds_read_b128 v[156:159], v2 offset:2048
	ds_read_b128 v[160:163], v2 offset:3072
	v_lshl_add_u64 v[226:227], s[2:3], 0, v[164:165]
	ds_read_b128 v[176:179], v189 offset:32768
	ds_read_b128 v[180:183], v189 offset:33792
	ds_read_b128 v[198:201], v189 offset:34816
	ds_read_b128 v[202:205], v189 offset:35840
	ds_read_b128 v[206:209], v189 offset:36864
	ds_read_b128 v[210:213], v189 offset:37888
	ds_read_b128 v[214:217], v189 offset:38912
	ds_read_b128 v[218:221], v189 offset:39936
	v_lshl_add_u64 v[226:227], s[2:3], 0, v[168:169]
	s_waitcnt vmcnt(8)
	s_waitcnt lgkmcnt(0)
	s_barrier
	s_waitcnt lgkmcnt(0)
	v_mfma_f32_16x16x32_bf16 v[128:131], v[132:135], v[176:179], v[128:131]
	v_mfma_f32_16x16x32_bf16 v[124:127], v[140:143], v[176:179], v[124:127]
	v_mfma_f32_16x16x32_bf16 v[112:115], v[132:135], v[198:201], v[112:115]
	v_mfma_f32_16x16x32_bf16 v[108:111], v[140:143], v[198:201], v[108:111]
	v_mfma_f32_16x16x32_bf16 v[96:99], v[132:135], v[206:209], v[96:99]
	v_mfma_f32_16x16x32_bf16 v[92:95], v[140:143], v[206:209], v[92:95]
	v_mfma_f32_16x16x32_bf16 v[80:83], v[132:135], v[214:217], v[80:83]
	v_mfma_f32_16x16x32_bf16 v[76:79], v[140:143], v[214:217], v[76:79]
	v_mfma_f32_16x16x32_bf16 v[128:131], v[136:139], v[180:183], v[128:131]
	v_mfma_f32_16x16x32_bf16 v[124:127], v[144:147], v[180:183], v[124:127]
	v_mfma_f32_16x16x32_bf16 v[112:115], v[136:139], v[202:205], v[112:115]
	v_mfma_f32_16x16x32_bf16 v[108:111], v[144:147], v[202:205], v[108:111]
	v_mfma_f32_16x16x32_bf16 v[96:99], v[136:139], v[210:213], v[96:99]
	v_mfma_f32_16x16x32_bf16 v[92:95], v[144:147], v[210:213], v[92:95]
	v_mfma_f32_16x16x32_bf16 v[80:83], v[136:139], v[218:221], v[80:83]
	v_mfma_f32_16x16x32_bf16 v[76:79], v[144:147], v[218:221], v[76:79]
	v_mfma_f32_16x16x32_bf16 v[120:123], v[148:151], v[176:179], v[120:123]
	v_mfma_f32_16x16x32_bf16 v[116:119], v[156:159], v[176:179], v[116:119]
	v_mfma_f32_16x16x32_bf16 v[104:107], v[148:151], v[198:201], v[104:107]
	v_mfma_f32_16x16x32_bf16 v[100:103], v[156:159], v[198:201], v[100:103]
	v_mfma_f32_16x16x32_bf16 v[88:91], v[148:151], v[206:209], v[88:91]
	v_mfma_f32_16x16x32_bf16 v[84:87], v[156:159], v[206:209], v[84:87]
	v_mfma_f32_16x16x32_bf16 v[72:75], v[148:151], v[214:217], v[72:75]
	v_mfma_f32_16x16x32_bf16 v[68:71], v[156:159], v[214:217], v[68:71]
	v_mfma_f32_16x16x32_bf16 v[120:123], v[152:155], v[180:183], v[120:123]
	v_mfma_f32_16x16x32_bf16 v[116:119], v[160:163], v[180:183], v[116:119]
	v_mfma_f32_16x16x32_bf16 v[104:107], v[152:155], v[202:205], v[104:107]
	v_mfma_f32_16x16x32_bf16 v[100:103], v[160:163], v[202:205], v[100:103]
	v_mfma_f32_16x16x32_bf16 v[88:91], v[152:155], v[210:213], v[88:91]
	v_mfma_f32_16x16x32_bf16 v[84:87], v[160:163], v[210:213], v[84:87]
	v_mfma_f32_16x16x32_bf16 v[72:75], v[152:155], v[218:221], v[72:75]
	v_mfma_f32_16x16x32_bf16 v[68:71], v[160:163], v[218:221], v[68:71]
	s_barrier
	s_add_u32 s98, s72, 0x80
	s_addc_u32 s99, s73, 0
	s_add_u32 s100, s74, 0x80
	s_addc_u32 s101, s75, 0
	s_add_i32 s0, s0, s80
	s_mov_b32 m0, s0
	s_nop 0
	global_load_lds_dwordx4 v166, s[98:99]
	s_add_i32 m0, s0, 0x2000
	s_add_u32 s2, s72, 0x40080
	s_addc_u32 s3, s73, 0
	s_add_i32 s0, s9, s80
	global_load_lds_dwordx4 v170, s[98:99]
	s_mov_b32 m0, s0
	s_nop 0
	global_load_lds_dwordx4 v166, s[2:3]
	s_add_i32 m0, s0, 0x2000
	s_nop 0
	global_load_lds_dwordx4 v170, s[2:3]
	s_mov_b32 m0, s92
	s_nop 0
	global_load_lds_dwordx4 v164, s[100:101]
	s_mov_b32 m0, s93
	s_nop 0
	global_load_lds_dwordx4 v168, s[100:101]
	v_lshl_add_u64 v[184:185], v[184:185], 0, s[26:27]
	ds_read_b128 v[176:179], v189 offset:49152
	ds_read_b128 v[180:183], v189 offset:50176
	ds_read_b128 v[198:201], v189 offset:51200
	ds_read_b128 v[202:205], v189 offset:52224
	ds_read_b128 v[206:209], v189 offset:53248
	ds_read_b128 v[210:213], v189 offset:54272
	ds_read_b128 v[214:217], v189 offset:55296
	ds_read_b128 v[218:221], v189 offset:56320
	v_lshl_add_u64 v[184:185], v[190:191], 0, s[26:27]
	v_lshl_add_u64 v[184:185], s[2:3], 0, v[166:167]
	v_lshl_add_u64 v[184:185], s[2:3], 0, v[170:171]
	v_lshl_add_u64 v[184:185], v[222:223], 0, s[26:27]
	v_lshl_add_u64 v[184:185], v[224:225], 0, s[26:27]
	s_waitcnt vmcnt(8)
	s_waitcnt lgkmcnt(0)
	s_barrier
	s_waitcnt lgkmcnt(0)
	v_mfma_f32_16x16x32_bf16 v[64:67], v[132:135], v[176:179], v[64:67]
	v_mfma_f32_16x16x32_bf16 v[60:63], v[140:143], v[176:179], v[60:63]
	v_mfma_f32_16x16x32_bf16 v[48:51], v[132:135], v[198:201], v[48:51]
	v_mfma_f32_16x16x32_bf16 v[44:47], v[140:143], v[198:201], v[44:47]
	v_mfma_f32_16x16x32_bf16 v[32:35], v[132:135], v[206:209], v[32:35]
	v_mfma_f32_16x16x32_bf16 v[28:31], v[140:143], v[206:209], v[28:31]
	v_mfma_f32_16x16x32_bf16 v[16:19], v[132:135], v[214:217], v[16:19]
	v_mfma_f32_16x16x32_bf16 v[12:15], v[140:143], v[214:217], v[12:15]
	v_mfma_f32_16x16x32_bf16 v[64:67], v[136:139], v[180:183], v[64:67]
	v_mfma_f32_16x16x32_bf16 v[60:63], v[144:147], v[180:183], v[60:63]
	v_mfma_f32_16x16x32_bf16 v[48:51], v[136:139], v[202:205], v[48:51]
	v_mfma_f32_16x16x32_bf16 v[44:47], v[144:147], v[202:205], v[44:47]
	v_mfma_f32_16x16x32_bf16 v[32:35], v[136:139], v[210:213], v[32:35]
	v_mfma_f32_16x16x32_bf16 v[28:31], v[144:147], v[210:213], v[28:31]
	v_mfma_f32_16x16x32_bf16 v[16:19], v[136:139], v[218:221], v[16:19]
	v_mfma_f32_16x16x32_bf16 v[12:15], v[144:147], v[218:221], v[12:15]
	v_mfma_f32_16x16x32_bf16 v[56:59], v[148:151], v[176:179], v[56:59]
	v_mfma_f32_16x16x32_bf16 v[52:55], v[156:159], v[176:179], v[52:55]
	v_mfma_f32_16x16x32_bf16 v[40:43], v[148:151], v[198:201], v[40:43]
	v_mfma_f32_16x16x32_bf16 v[36:39], v[156:159], v[198:201], v[36:39]
	v_mfma_f32_16x16x32_bf16 v[24:27], v[148:151], v[206:209], v[24:27]
	v_mfma_f32_16x16x32_bf16 v[20:23], v[156:159], v[206:209], v[20:23]
	v_mfma_f32_16x16x32_bf16 v[8:11], v[148:151], v[214:217], v[8:11]
	v_mfma_f32_16x16x32_bf16 v[4:7], v[156:159], v[214:217], v[4:7]
	v_mfma_f32_16x16x32_bf16 v[56:59], v[152:155], v[180:183], v[56:59]
	v_mfma_f32_16x16x32_bf16 v[52:55], v[160:163], v[180:183], v[52:55]
	v_mfma_f32_16x16x32_bf16 v[40:43], v[152:155], v[202:205], v[40:43]
	v_mfma_f32_16x16x32_bf16 v[36:39], v[160:163], v[202:205], v[36:39]
	v_mfma_f32_16x16x32_bf16 v[24:27], v[152:155], v[210:213], v[24:27]
	v_mfma_f32_16x16x32_bf16 v[20:23], v[160:163], v[210:213], v[20:23]
	v_mfma_f32_16x16x32_bf16 v[8:11], v[152:155], v[218:221], v[8:11]
	v_mfma_f32_16x16x32_bf16 v[4:7], v[160:163], v[218:221], v[4:7]
	s_barrier
	s_add_i32 vcc_hi, vcc_hi, 2
	s_add_u32 s70, s70, 0x100
	s_addc_u32 s71, s71, 0
	s_add_u32 s63, s63, 0x100
	s_addc_u32 vcc_lo, vcc_lo, 0
	s_cmp_gt_u32 vcc_hi, 13
	s_cbranch_scc0 .LBB0_920
	s_and_b64 vcc, exec, s[52:53]
	s_cbranch_vccz .LBB0_923
	s_barrier

.LBB0_1177:
	s_setprio 0
	v_readlane_b32 s14, v254, 30
	v_readlane_b32 s0, v253, 5
	s_add_i32 s14, s14, 1
	v_readlane_b32 s1, v253, 6
	v_readlane_b32 s3, v253, 8
	v_readlane_b32 s40, v254, 22
	v_readlane_b32 s30, v254, 24
	s_cmp_ge_i32 s14, s3
	s_mov_b64 s[0:1], -1
	v_readlane_b32 s41, v254, 23
	v_readlane_b32 s31, v254, 25
	v_readlane_b32 s2, v253, 7
	s_cbranch_scc0 .LBB0_1178
	s_getpc_b64 s[98:99]
